# GEMM1 unit boundary: next bias loads issued before epilogue stores (dead frag regs), boundary vmcnt(0)->vmcnt(16), first K-tile no-op waits skipped; + no entry grid.sync
# speedup vs baseline: 1.0133x; 1.0133x over previous
; #define PG8_WAIT_V(n) asm volatile("s_waitcnt vmcnt(" #n ")" ::: "memory")
; template <class Epi, class Sched, bool ALIGN_EPI = false, bool SP2 = false>
; __device__ __forceinline__ void gemm_phase(PG8_LAS unsigned char* lds, const Gemm g, const Sched& S, const Epi& E) {
;     int tid_ = threadIdx.x; asm volatile("" : "+v"(tid_));
;     const int tid = tid_, wid = __builtin_amdgcn_readfirstlane(tid >> 6), lane = tid & 63, wr = wid >> 2, wc = wid & 3, fr = lane & 15, fq = lane >> 4;
;     int K_ = g.K; asm volatile("" : "+s"(K_));
;     const int K = K_, nt = K / BK;
;     unsigned voffA[2], voffB[2];
; #pragma unroll
;     for (int i = 0; i < 2; ++i) { int R, C; stage_rc(tid * 16 + i * 8192, R, C); const int Rb = Epi::PERM ? ((R & ~31) + perm32(R & 31)) : R;
;         voffA[i] = (unsigned)(R * K + C) * 2u; voffB[i] = (unsigned)(Rb * K + C) * 2u; }
;     const size_t kstep = (size_t)(BK * 2);
;     const size_t hstep = (size_t)HALF * K * 2;
;     const size_t tstep = 2 * hstep;
;     const unsigned ldsw = (unsigned)wid * 1024u;
;     const int aoff = lds_byte(wr * 64 + fr, fq * 8), boff = lds_byte(wc * 32 + fr, fq * 8);
;     ...
;     Unit cur, nxt; int ui = 0;
;     if (!S.next(0, cur)) return;
;     f32x4 acc[2][2][4][2];
;     f32x4 ini[2][2];
; #pragma unroll
;     for (int b = 0; b < 2; ++b)
; #pragma unroll
;         for (int n = 0; n < 2; ++n) ini[b][n] = (f32x4){0.f, 0.f, 0.f, 0.f};
;     if constexpr (Epi::ACC_INIT) E.acc_init(ini, cur);
; #pragma unroll
;     for (int a = 0; a < 2; ++a)
; #pragma unroll
;         for (int b = 0; b < 2; ++b)
; #pragma unroll
;             for (int m = 0; m < 4; ++m)
; #pragma unroll
;                 for (int n = 0; n < 2; ++n) acc[a][b][m][n] = ini[b][n];
;     bf16x8 At[4][2], B0[2][2], B1[2][2];
;     const char* cA = (const char*)g.A + (size_t)cur.pm * tstep; const char* cB = (const char*)g.Bt + (size_t)cur.pn * tstep;
;     S.a_ready(cur);
;     if constexpr (SP2) {
;         PG8_STAGE(PG8_SB(0, 0), cB, voffB); PG8_STAGE(PG8_SB(0, 1), cB + hstep, voffB); PG8_STAGE(PG8_SA(0, 0), cA, voffA); PG8_STAGE(PG8_SA(0, 1), cA + hstep, voffA);
;         if (wr == 1) PG8_BAR;
;         PG8_WAIT_V(2); PG8_BAR;
;         PG8_STAGE(PG8_SB(1, 0), cB + kstep, voffB); PG8_STAGE(PG8_SA(1, 0), cA + kstep, voffA); PG8_STAGE(PG8_SB(1, 1), cB + hstep + kstep, voffB);
;         PG8_WAIT_V(6); PG8_BAR;
;     } else {
.LBB0_386:
	s_and_b64 vcc, exec, s[38:39]
	s_cbranch_vccz .LBB0_416
	v_readlane_b32 s12, v253, 29
	s_waitcnt vmcnt(0)
	v_mov_b32_e32 v16, v212
	v_readlane_b32 s13, v253, 30
	s_movk_i32 s38, 0x400
	v_readfirstlane_b32 s50, v16
	s_andn2_b64 vcc, exec, s[12:13]
	s_cbranch_vccnz .LBB0_416
	s_waitcnt vmcnt(0)
	v_lshlrev_b32_e32 v0, 4, v16
	s_waitcnt lgkmcnt(0)
	v_add_u32_e32 v1, 0x2000, v0
	v_ashrrev_i32_e32 v2, 31, v1
	v_lshrrev_b32_e32 v2, 22, v2
	v_add_u32_e32 v2, v1, v2
	s_ashr_i32 s73, s72, 31
	v_ashrrev_i32_e32 v2, 10, v2
	s_lshl_b64 s[12:13], s[72:73], 3
	v_readlane_b32 s16, v253, 0
	s_waitcnt lgkmcnt(2)
	v_mul_i32_i24_e32 v3, 0x400, v2
	v_readlane_b32 s17, v253, 1
	s_add_u32 s12, s16, s12
	v_sub_u32_e32 v1, v1, v3
	s_addc_u32 s13, s17, s13
	v_lshrrev_b32_e32 v3, 4, v1
	s_load_dwordx2 s[12:13], s[12:13], 0x10
	v_bitop3_b32 v1, v3, v1, 32 bitop3:0x6c
	v_ashrrev_i32_e32 v3, 31, v1
	v_lshrrev_b32_e32 v3, 26, v3
	v_add_u32_e32 v3, v1, v3
	s_waitcnt vmcnt(0) lgkmcnt(0)
	v_lshlrev_b32_e32 v5, 3, v2
	s_mul_i32 s0, s80, 0x6020
	v_ashrrev_i32_e32 v4, 6, v3
	v_and_b32_e32 v5, -16, v5
	v_lshlrev_b32_e32 v2, 5, v2
	s_mul_hi_i32 s6, s80, 0x6020
	s_add_u32 s0, s12, s0
	v_add_u32_e32 v5, v4, v5
	v_and_b32_e32 v17, 32, v2
	v_and_b32_e32 v2, 0xc0, v3
	s_addc_u32 s6, s13, s6
	v_and_b32_e32 v4, 3, v4
	s_mov_b32 s13, 0x7fffffe0
	v_lshrrev_b32_e32 v6, 2, v5
	v_lshlrev_b32_e32 v7, 1, v5
	v_sub_u32_e32 v1, v1, v2
	v_and_or_b32 v4, v5, s13, v4
	v_and_b32_e32 v6, 4, v6
	v_and_b32_e32 v7, 24, v7
	v_ashrrev_i16_sdwa v1, v222, sext(v1) dst_sel:DWORD dst_unused:UNUSED_PAD src0_sel:DWORD src1_sel:BYTE_0
	v_or3_b32 v4, v4, v6, v7
	v_bfe_i32 v18, v1, 0, 16
	v_mul_lo_u32 v4, v4, s38
	v_add_u32_e32 v1, v17, v18
	v_mul_lo_u32 v19, v5, s38
	v_add_lshl_u32 v130, v4, v1, 1
	v_add_lshl_u32 v132, v1, v19, 1
	v_bfe_i32 v1, v16, 27, 1
	v_lshrrev_b32_e32 v1, 22, v1
	v_add_u32_e32 v1, v0, v1
	v_and_b32_e32 v1, 0xfffffc00, v1
	v_sub_u32_e32 v0, v0, v1
	v_lshrrev_b32_e32 v1, 4, v0
	v_ashrrev_i32_e32 v3, 31, v16
	v_bitop3_b32 v0, v1, v0, 32 bitop3:0x6c
	v_lshrrev_b32_e32 v3, 26, v3
	v_ashrrev_i32_e32 v1, 31, v0
	v_add_u32_e32 v3, v16, v3
	v_lshrrev_b32_e32 v1, 26, v1
	v_ashrrev_i32_e32 v3, 6, v3
	v_add_u32_e32 v1, v0, v1
	v_lshlrev_b32_e32 v4, 3, v3
	v_ashrrev_i32_e32 v2, 6, v1
	v_and_b32_e32 v4, -16, v4
	v_add_u32_e32 v4, v2, v4
	v_and_b32_e32 v1, 0xc0, v1
	v_writelane_b32 v252, s76, 50
	v_and_b32_e32 v2, 3, v2
	v_lshrrev_b32_e32 v5, 2, v4
	v_lshlrev_b32_e32 v6, 1, v4
	v_sub_u32_e32 v0, v0, v1
	v_writelane_b32 v252, s77, 51
	s_ashr_i32 s48, s50, 6
	s_ashr_i32 s39, s38, 31
	v_and_or_b32 v2, v4, s13, v2
	v_and_b32_e32 v5, 4, v5
	v_and_b32_e32 v6, 24, v6
	v_lshlrev_b32_e32 v3, 5, v3
	v_ashrrev_i16_sdwa v0, v222, sext(v0) dst_sel:DWORD dst_unused:UNUSED_PAD src0_sel:DWORD src1_sel:BYTE_0
	s_ashr_i32 s49, s50, 8
	s_lshl_b64 s[42:43], s[38:39], 8
	s_lshl_b64 s[44:45], s[38:39], 9
	s_lshl_b32 s12, s48, 10
	v_or3_b32 v2, v2, v5, v6
	v_and_b32_e32 v20, 32, v3
	v_bfe_i32 v21, v0, 0, 16
	v_readlane_b32 s16, v252, 40
	v_mul_lo_u32 v2, v2, s38
	v_add_u32_e32 v0, v20, v21
	v_mul_lo_u32 v22, v4, s38
	v_readlane_b32 s17, v252, 41
	s_add_u32 s16, s0, s16
	v_add_lshl_u32 v96, v2, v0, 1
	v_add_lshl_u32 v134, v0, v22, 1
	v_mov_b32_e32 v0, v212
	s_addc_u32 s17, s6, s17
	v_readlane_b32 s20, v252, 42
	s_add_u32 s16, s16, s20
	v_readfirstlane_b32 s13, v0
	s_addc_u32 s17, s17, 0
	s_lshl_b32 s13, s13, 1
	s_and_b32 s13, s13, 0x180
	s_add_u32 s16, s16, s13
	v_lshlrev_b32_e32 v0, 1, v0
	s_addc_u32 s17, s17, 0
	v_and_b32_e32 v4, 0x60, v0
	v_readlane_b32 s13, v252, 37
	v_readlane_b32 s20, v252, 36
	global_load_dwordx4 v[182:185], v4, s[16:17] offset:16
	global_load_dwordx4 v[186:189], v4, s[16:17]
	global_load_dwordx4 v[174:177], v4, s[16:17] offset:528
	s_nop 0
	global_load_dwordx4 v[178:181], v4, s[16:17] offset:512
	s_mul_i32 s13, s44, s13
	s_mul_hi_u32 s16, s44, s20
	s_add_i32 s13, s16, s13
	s_lshr_b64 s[16:17], s[38:39], 23
	v_readlane_b32 s24, v252, 34
	s_mul_i32 s17, s16, s20
	v_readlane_b32 s25, v252, 35
	s_add_i32 s21, s13, s17
	s_mul_i32 s13, s44, s25
	s_mul_hi_u32 s17, s44, s24
	s_add_i32 s13, s17, s13
	s_mul_i32 s16, s16, s24
	s_add_i32 s13, s13, s16
	s_mul_i32 s16, s44, s24
	v_readlane_b32 s24, v253, 27
	v_readlane_b32 s25, v253, 28
	s_add_u32 s62, s24, s16
	s_addc_u32 s63, s25, s13
	s_add_i32 s13, s12, 0x10000
	s_add_i32 s16, s12, 0x12000
	s_mov_b32 m0, s13
	s_add_u32 s40, s62, s42
	s_mul_i32 s22, s44, s20
	global_load_lds_dwordx4 v96, s[62:63]
	s_mov_b32 m0, s16
	s_addc_u32 s41, s63, s43
	s_add_i32 s17, s12, 0x14000
	s_add_i32 s20, s12, 0x16000
	global_load_lds_dwordx4 v130, s[62:63]
	s_mov_b32 m0, s17
	s_add_u32 s60, s82, s22
	global_load_lds_dwordx4 v96, s[40:41]
	s_mov_b32 m0, s20
	s_addc_u32 s61, s83, s21
	s_add_i32 s21, s12, 0x2000
	global_load_lds_dwordx4 v130, s[40:41]
	s_mov_b32 m0, s12
	s_add_u32 s46, s60, s42
	global_load_lds_dwordx4 v134, s[60:61]
	s_mov_b32 m0, s21
	s_addc_u32 s47, s61, s43
	s_add_i32 s22, s12, 0x4000
	global_load_lds_dwordx4 v132, s[60:61]
	s_mov_b32 m0, s22
	s_add_i32 s23, s12, 0x6000
	global_load_lds_dwordx4 v134, s[46:47]
	s_mov_b32 m0, s23
	s_cmp_eq_u32 s49, 1
	global_load_lds_dwordx4 v132, s[46:47]
	s_mov_b32 s86, s72
	s_cselect_b64 s[46:47], -1, 0
	s_cmp_lg_u32 s49, 1
	s_cbranch_scc1 .LBB0_390
	s_barrier

; #define PG8_STAGE(bufoff, gbase, voff) do { _Pragma("unroll") for (int _i = 0; _i < 2; ++_i) \
;         __builtin_amdgcn_global_load_lds((const unsigned*)((const char*)(gbase) + (voff)[_i]), (PG8_LAS unsigned*)(lds + (bufoff) + ldsw + _i * 8192), 16, 0, 0); } while (0)
; #define PG8_LDA(dst, b, h) do { _Pragma("unroll") for (int m = 0; m < 4; ++m) _Pragma("unroll") for (int k = 0; k < 2; ++k) dst[m][k] = *(const PG8_LAS bf16x8*)(lds + PG8_SA(b, h) + aoff + m * 2048 + k * 1024); } while (0)
; #define PG8_LDB(dst, b, h) do { _Pragma("unroll") for (int n = 0; n < 2; ++n) _Pragma("unroll") for (int k = 0; k < 2; ++k) dst[n][k] = *(const PG8_LAS bf16x8*)(lds + PG8_SB(b, h) + boff + n * 2048 + k * 1024); } while (0)
; #define PG8_MMA(ai, bj, At, Bt) do { __builtin_amdgcn_s_setprio(1); _Pragma("unroll") for (int m = 0; m < 4; ++m) _Pragma("unroll") for (int n = 0; n < 2; ++n) _Pragma("unroll") for (int k = 0; k < 2; ++k) \
;         acc[ai][bj][m][n] = __builtin_amdgcn_mfma_f32_16x16x32_bf16(Bt[n][k], At[m][k], acc[ai][bj][m][n], 0, 0, 0); __builtin_amdgcn_s_setprio(0); } while (0)
; #define PG8_WAIT_V(n) asm volatile("s_waitcnt vmcnt(" #n ")" ::: "memory")
; #define PG8_WAIT_L(n) asm volatile("s_waitcnt lgkmcnt(" #n ")" ::: "memory")
; #define PG8_BAR __builtin_amdgcn_s_barrier()
; #define PG8_SCHED __builtin_amdgcn_sched_barrier(0)
; template <class Epi, class Sched, bool ALIGN_EPI = false, bool SP2 = false>
; __device__ __forceinline__ void gemm_phase(PG8_LAS unsigned char* lds, const Gemm g, const Sched& S, const Epi& E) {
;     ...
;             PG8_LDB(B0, 0, 0); PG8_LDB(B1, 0, 1); PG8_SCHED; PG8_LDA(At, 0, 0); PG8_STAGE(PG8_SA(1, 1), a1 + hstep, voffA);
;             PG8_WAIT_V(8); PG8_WAIT_L(0); PG8_BAR; PG8_MMA(0, 0, At, B0); PG8_MMA(0, 1, At, B1); PG8_BAR; PG8_SCHED;
;     ...
; #pragma unroll
;         for (int a = 0; a < 2; ++a)
; #pragma unroll
;             for (int b = 0; b < 2; ++b)
; #pragma unroll
;                 for (int m = 0; m < 4; ++m)
; #pragma unroll
;                     for (int n = 0; n < 2; ++n) acc[a][b][m][n] = ini[b][n];
.LBB0_398:
	s_add_u32 s60, s60, 0x80
	s_addc_u32 s61, s61, 0
	s_add_u32 s55, s62, 0x100
	s_waitcnt vmcnt(16)
	v_mov_b64_e32 v[0:1], v[174:175]
	v_mov_b64_e32 v[2:3], v[176:177]
	v_mov_b64_e32 v[4:5], v[178:179]
	v_mov_b64_e32 v[6:7], v[180:181]
	v_mov_b64_e32 v[8:9], v[182:183]
	v_mov_b64_e32 v[10:11], v[184:185]
	v_mov_b64_e32 v[12:13], v[186:187]
	v_mov_b64_e32 v[14:15], v[188:189]
	v_mov_b64_e32 v[18:19], v[2:3]
	v_mov_b64_e32 v[22:23], v[6:7]
	v_mov_b64_e32 v[26:27], v[2:3]
	v_mov_b64_e32 v[30:31], v[6:7]
	v_mov_b64_e32 v[34:35], v[2:3]
	v_mov_b64_e32 v[38:39], v[6:7]
	v_mov_b64_e32 v[74:75], v[10:11]
	v_mov_b64_e32 v[78:79], v[14:15]
	v_mov_b64_e32 v[82:83], v[10:11]
	v_mov_b64_e32 v[86:87], v[14:15]
	v_mov_b64_e32 v[90:91], v[10:11]
	v_mov_b64_e32 v[94:95], v[14:15]
	v_mov_b64_e32 v[42:43], v[2:3]
	v_mov_b64_e32 v[46:47], v[6:7]
	v_mov_b64_e32 v[50:51], v[2:3]
	v_mov_b64_e32 v[54:55], v[6:7]
	v_mov_b64_e32 v[58:59], v[2:3]
	v_mov_b64_e32 v[62:63], v[6:7]
	v_mov_b64_e32 v[66:67], v[2:3]
	v_mov_b64_e32 v[70:71], v[6:7]
	v_mov_b64_e32 v[100:101], v[10:11]
	v_mov_b64_e32 v[104:105], v[14:15]
	v_mov_b64_e32 v[108:109], v[10:11]
	v_mov_b64_e32 v[112:113], v[14:15]
	v_mov_b64_e32 v[116:117], v[10:11]
	v_mov_b64_e32 v[120:121], v[14:15]
	v_mov_b64_e32 v[124:125], v[10:11]
	v_mov_b64_e32 v[128:129], v[14:15]
	s_addc_u32 s73, s63, 0
	s_mov_b32 s62, 0
	v_mov_b64_e32 v[16:17], v[0:1]
	v_mov_b64_e32 v[20:21], v[4:5]
	v_mov_b64_e32 v[24:25], v[0:1]
	v_mov_b64_e32 v[28:29], v[4:5]
	v_mov_b64_e32 v[32:33], v[0:1]
	v_mov_b64_e32 v[36:37], v[4:5]
	v_mov_b64_e32 v[72:73], v[8:9]
	v_mov_b64_e32 v[76:77], v[12:13]
	v_mov_b64_e32 v[80:81], v[8:9]
	v_mov_b64_e32 v[84:85], v[12:13]
	v_mov_b64_e32 v[88:89], v[8:9]
	v_mov_b64_e32 v[92:93], v[12:13]
	v_mov_b64_e32 v[40:41], v[0:1]
	v_mov_b64_e32 v[44:45], v[4:5]
	v_mov_b64_e32 v[48:49], v[0:1]
	v_mov_b64_e32 v[52:53], v[4:5]
	v_mov_b64_e32 v[56:57], v[0:1]
	v_mov_b64_e32 v[60:61], v[4:5]
	v_mov_b64_e32 v[64:65], v[0:1]
	v_mov_b64_e32 v[68:69], v[4:5]
	v_mov_b64_e32 v[98:99], v[8:9]
	v_mov_b64_e32 v[102:103], v[12:13]
	v_mov_b64_e32 v[106:107], v[8:9]
	v_mov_b64_e32 v[110:111], v[12:13]
	v_mov_b64_e32 v[114:115], v[8:9]
	v_mov_b64_e32 v[118:119], v[12:13]
	v_mov_b64_e32 v[122:123], v[8:9]
	v_mov_b64_e32 v[126:127], v[12:13]
.LBB0_399:
	v_or_b32_e32 v142, 0x10000, v141
	v_add_u32_e32 v146, 0x10400, v141
	v_add_u32_e32 v150, 0x10800, v141
	v_add_u32_e32 v154, 0x10c00, v141
	v_or_b32_e32 v158, 0x14000, v141
	v_add_u32_e32 v162, 0x14400, v141
	v_add_u32_e32 v166, 0x14800, v141
	v_add_u32_e32 v170, 0x14c00, v141
	s_add_i32 s74, s62, 2
	ds_read_b128 v[142:145], v142
	ds_read_b128 v[146:149], v146
	ds_read_b128 v[150:153], v150
	ds_read_b128 v[154:157], v154
	ds_read_b128 v[158:161], v158
	ds_read_b128 v[162:165], v162
	ds_read_b128 v[166:169], v166
	ds_read_b128 v[170:173], v170
	s_add_u32 s75, s60, 0x80
	s_addc_u32 s63, s61, 0
	s_cmp_eq_u32 s68, s62
	s_cselect_b32 s62, s40, s75
	s_cselect_b32 s63, s41, s63
	s_cselect_b32 s77, s53, s73
	s_cselect_b32 s76, s52, s55
	v_lshl_add_u64 v[210:211], s[60:61], 0, v[136:137]
	s_add_i32 m0, s12, 0xc000
	ds_read_b128 v[174:177], v140
	ds_read_b128 v[178:181], v140 offset:1024
	ds_read_b128 v[182:185], v140 offset:2048
	ds_read_b128 v[186:189], v140 offset:3072
	ds_read_b128 v[190:193], v140 offset:4096
	ds_read_b128 v[202:205], v140 offset:5120
	ds_read_b128 v[206:209], v140 offset:6144
	ds_read_b128 v[230:233], v140 offset:7168
	global_load_lds_dwordx4 v[210:211], off
	v_lshl_add_u64 v[210:211], s[60:61], 0, v[138:139]
	s_add_i32 m0, s12, 0xe000
	s_nop 0
	global_load_lds_dwordx4 v[210:211], off
	s_cmp_eq_u32 s74, 2
	s_cbranch_scc1 .Lw1_skip
	s_waitcnt vmcnt(8)
.Lw1_skip:
	s_waitcnt lgkmcnt(0)
	s_barrier
	s_setprio 1
	s_waitcnt lgkmcnt(0)
	v_mfma_f32_16x16x32_bf16 v[126:129], v[142:145], v[174:177], v[126:129]
	v_mfma_f32_16x16x32_bf16 v[122:125], v[150:153], v[174:177], v[122:125]
	v_mfma_f32_16x16x32_bf16 v[118:121], v[142:145], v[182:185], v[118:121]
	v_mfma_f32_16x16x32_bf16 v[114:117], v[150:153], v[182:185], v[114:117]
	v_mfma_f32_16x16x32_bf16 v[110:113], v[142:145], v[190:193], v[110:113]
	v_mfma_f32_16x16x32_bf16 v[106:109], v[150:153], v[190:193], v[106:109]
	v_mfma_f32_16x16x32_bf16 v[102:105], v[142:145], v[206:209], v[102:105]
	v_mfma_f32_16x16x32_bf16 v[98:101], v[150:153], v[206:209], v[98:101]
	v_mfma_f32_16x16x32_bf16 v[126:129], v[146:149], v[178:181], v[126:129]
	v_mfma_f32_16x16x32_bf16 v[122:125], v[154:157], v[178:181], v[122:125]
	v_mfma_f32_16x16x32_bf16 v[118:121], v[146:149], v[186:189], v[118:121]
	v_mfma_f32_16x16x32_bf16 v[114:117], v[154:157], v[186:189], v[114:117]
	v_mfma_f32_16x16x32_bf16 v[110:113], v[146:149], v[202:205], v[110:113]
	v_mfma_f32_16x16x32_bf16 v[106:109], v[154:157], v[202:205], v[106:109]
	v_mfma_f32_16x16x32_bf16 v[102:105], v[146:149], v[230:233], v[102:105]
	v_mfma_f32_16x16x32_bf16 v[98:101], v[154:157], v[230:233], v[98:101]
	s_setprio 0
	s_setprio 1
	v_mfma_f32_16x16x32_bf16 v[68:71], v[158:161], v[174:177], v[68:71]
	v_mfma_f32_16x16x32_bf16 v[64:67], v[166:169], v[174:177], v[64:67]
	v_mfma_f32_16x16x32_bf16 v[60:63], v[158:161], v[182:185], v[60:63]
	v_mfma_f32_16x16x32_bf16 v[56:59], v[166:169], v[182:185], v[56:59]
	v_mfma_f32_16x16x32_bf16 v[52:55], v[158:161], v[190:193], v[52:55]
	v_mfma_f32_16x16x32_bf16 v[48:51], v[166:169], v[190:193], v[48:51]
	v_mfma_f32_16x16x32_bf16 v[44:47], v[158:161], v[206:209], v[44:47]
	v_mfma_f32_16x16x32_bf16 v[40:43], v[166:169], v[206:209], v[40:43]
	v_mfma_f32_16x16x32_bf16 v[68:71], v[162:165], v[178:181], v[68:71]
	v_mfma_f32_16x16x32_bf16 v[64:67], v[170:173], v[178:181], v[64:67]
	v_mfma_f32_16x16x32_bf16 v[60:63], v[162:165], v[186:189], v[60:63]
	v_mfma_f32_16x16x32_bf16 v[56:59], v[170:173], v[186:189], v[56:59]
	v_mfma_f32_16x16x32_bf16 v[52:55], v[162:165], v[202:205], v[52:55]
	v_mfma_f32_16x16x32_bf16 v[48:51], v[170:173], v[202:205], v[48:51]
	v_mfma_f32_16x16x32_bf16 v[44:47], v[162:165], v[230:233], v[44:47]
	v_mfma_f32_16x16x32_bf16 v[40:43], v[170:173], v[230:233], v[40:43]
	s_setprio 0
	s_barrier
; #define PG8_STAGE(bufoff, gbase, voff) do { _Pragma("unroll") for (int _i = 0; _i < 2; ++_i) \
;         __builtin_amdgcn_global_load_lds((const unsigned*)((const char*)(gbase) + (voff)[_i]), (PG8_LAS unsigned*)(lds + (bufoff) + ldsw + _i * 8192), 16, 0, 0); } while (0)
; #define PG8_LDA(dst, b, h) do { _Pragma("unroll") for (int m = 0; m < 4; ++m) _Pragma("unroll") for (int k = 0; k < 2; ++k) dst[m][k] = *(const PG8_LAS bf16x8*)(lds + PG8_SA(b, h) + aoff + m * 2048 + k * 1024); } while (0)
; #define PG8_LDB(dst, b, h) do { _Pragma("unroll") for (int n = 0; n < 2; ++n) _Pragma("unroll") for (int k = 0; k < 2; ++k) dst[n][k] = *(const PG8_LAS bf16x8*)(lds + PG8_SB(b, h) + boff + n * 2048 + k * 1024); } while (0)
; #define PG8_MMA(ai, bj, At, Bt) do { __builtin_amdgcn_s_setprio(1); _Pragma("unroll") for (int m = 0; m < 4; ++m) _Pragma("unroll") for (int n = 0; n < 2; ++n) _Pragma("unroll") for (int k = 0; k < 2; ++k) \
;         acc[ai][bj][m][n] = __builtin_amdgcn_mfma_f32_16x16x32_bf16(Bt[n][k], At[m][k], acc[ai][bj][m][n], 0, 0, 0); __builtin_amdgcn_s_setprio(0); } while (0)
; #define PG8_WAIT_V(n) asm volatile("s_waitcnt vmcnt(" #n ")" ::: "memory")
; #define PG8_WAIT_L(n) asm volatile("s_waitcnt lgkmcnt(" #n ")" ::: "memory")
; #define PG8_BAR __builtin_amdgcn_s_barrier()
; #define PG8_SCHED __builtin_amdgcn_sched_barrier(0)
; template <class Epi, class Sched, bool ALIGN_EPI = false, bool SP2 = false>
; __device__ __forceinline__ void gemm_phase(PG8_LAS unsigned char* lds, const Gemm g, const Sched& S, const Epi& E) {
;     ...
;             PG8_LDA(At, 0, 1); PG8_STAGE(PG8_SB(0, 0), b2, voffB); PG8_STAGE(PG8_SB(0, 1), b2 + hstep, voffB); PG8_STAGE(PG8_SA(0, 0), a2, voffA);
;             PG8_WAIT_V(8); PG8_WAIT_L(0); PG8_BAR; PG8_MMA(1, 0, At, B0); PG8_MMA(1, 1, At, B1); PG8_BAR; PG8_SCHED;
;             PG8_LDB(B0, 1, 0); PG8_LDB(B1, 1, 1); PG8_SCHED; PG8_LDA(At, 1, 0); PG8_STAGE(PG8_SA(0, 1), a2 + hstep, voffA);
;             PG8_WAIT_V(8); PG8_WAIT_L(0); PG8_BAR; PG8_MMA(0, 0, At, B0); PG8_MMA(0, 1, At, B1); PG8_BAR; PG8_SCHED;
;             PG8_LDA(At, 1, 1); PG8_STAGE(PG8_SB(1, 0), b3, voffB); PG8_STAGE(PG8_SB(1, 1), b3 + hstep, voffB); PG8_STAGE(PG8_SA(1, 0), a3, voffA);
	s_mov_b32 m0, s13
	v_lshl_add_u64 v[210:211], s[76:77], 0, v[96:97]
	v_lshl_add_u64 v[234:235], s[76:77], 0, v[130:131]
	s_add_u32 s76, s76, s42
	ds_read_b128 v[174:177], v140 offset:16384
	ds_read_b128 v[178:181], v140 offset:17408
	ds_read_b128 v[182:185], v140 offset:18432
	ds_read_b128 v[186:189], v140 offset:19456
	ds_read_b128 v[190:193], v140 offset:20480
	ds_read_b128 v[202:205], v140 offset:21504
	ds_read_b128 v[206:209], v140 offset:22528
	ds_read_b128 v[230:233], v140 offset:23552
	global_load_lds_dwordx4 v[210:211], off
	s_mov_b32 m0, s16
	s_addc_u32 s77, s77, s43
	global_load_lds_dwordx4 v[234:235], off
	v_lshl_add_u64 v[236:237], s[76:77], 0, v[96:97]
	s_mov_b32 m0, s17
	v_lshl_add_u64 v[238:239], s[76:77], 0, v[130:131]
	global_load_lds_dwordx4 v[236:237], off
	s_mov_b32 m0, s20
	v_lshl_add_u64 v[240:241], s[62:63], 0, v[134:135]
	global_load_lds_dwordx4 v[238:239], off
	s_mov_b32 m0, s12
	v_lshl_add_u64 v[242:243], s[62:63], 0, v[132:133]
	global_load_lds_dwordx4 v[240:241], off
	s_mov_b32 m0, s21
	s_nop 0
	global_load_lds_dwordx4 v[242:243], off
	s_cmp_lg_u32 s74, 2
	s_cbranch_scc1 .Lw2_do
	s_cmp_gt_u32 s69, 1
	s_cbranch_scc1 .Lw2_skip
.Lw2_do:
	s_waitcnt vmcnt(8)
.Lw2_skip:
	s_waitcnt lgkmcnt(0)
	s_barrier
	s_setprio 1
	s_waitcnt lgkmcnt(0)
	v_mfma_f32_16x16x32_bf16 v[92:95], v[142:145], v[174:177], v[92:95]
	v_mfma_f32_16x16x32_bf16 v[88:91], v[150:153], v[174:177], v[88:91]
	v_mfma_f32_16x16x32_bf16 v[84:87], v[142:145], v[182:185], v[84:87]
	v_mfma_f32_16x16x32_bf16 v[80:83], v[150:153], v[182:185], v[80:83]
	v_mfma_f32_16x16x32_bf16 v[76:79], v[142:145], v[190:193], v[76:79]
	v_mfma_f32_16x16x32_bf16 v[72:75], v[150:153], v[190:193], v[72:75]
	v_mfma_f32_16x16x32_bf16 v[12:15], v[142:145], v[206:209], v[12:15]
	v_mfma_f32_16x16x32_bf16 v[8:11], v[150:153], v[206:209], v[8:11]
	v_mfma_f32_16x16x32_bf16 v[92:95], v[146:149], v[178:181], v[92:95]
	v_mfma_f32_16x16x32_bf16 v[88:91], v[154:157], v[178:181], v[88:91]
	v_mfma_f32_16x16x32_bf16 v[84:87], v[146:149], v[186:189], v[84:87]
	v_mfma_f32_16x16x32_bf16 v[80:83], v[154:157], v[186:189], v[80:83]
	v_mfma_f32_16x16x32_bf16 v[76:79], v[146:149], v[202:205], v[76:79]
	v_mfma_f32_16x16x32_bf16 v[72:75], v[154:157], v[202:205], v[72:75]
	v_mfma_f32_16x16x32_bf16 v[12:15], v[146:149], v[230:233], v[12:15]
	v_mfma_f32_16x16x32_bf16 v[8:11], v[154:157], v[230:233], v[8:11]
	s_setprio 0
	s_setprio 1
	v_mfma_f32_16x16x32_bf16 v[36:39], v[158:161], v[174:177], v[36:39]
	v_mfma_f32_16x16x32_bf16 v[32:35], v[166:169], v[174:177], v[32:35]
	v_mfma_f32_16x16x32_bf16 v[28:31], v[158:161], v[182:185], v[28:31]
	v_mfma_f32_16x16x32_bf16 v[24:27], v[166:169], v[182:185], v[24:27]
	v_mfma_f32_16x16x32_bf16 v[20:23], v[158:161], v[190:193], v[20:23]
	v_mfma_f32_16x16x32_bf16 v[16:19], v[166:169], v[190:193], v[16:19]
	v_mfma_f32_16x16x32_bf16 v[4:7], v[158:161], v[206:209], v[4:7]
	v_mfma_f32_16x16x32_bf16 v[0:3], v[166:169], v[206:209], v[0:3]
	v_mfma_f32_16x16x32_bf16 v[36:39], v[162:165], v[178:181], v[36:39]
	v_mfma_f32_16x16x32_bf16 v[32:35], v[170:173], v[178:181], v[32:35]
	v_mfma_f32_16x16x32_bf16 v[28:31], v[162:165], v[186:189], v[28:31]
	v_mfma_f32_16x16x32_bf16 v[24:27], v[170:173], v[186:189], v[24:27]
	v_mfma_f32_16x16x32_bf16 v[20:23], v[162:165], v[202:205], v[20:23]
	v_mfma_f32_16x16x32_bf16 v[16:19], v[170:173], v[202:205], v[16:19]
	v_mfma_f32_16x16x32_bf16 v[4:7], v[162:165], v[230:233], v[4:7]
	v_mfma_f32_16x16x32_bf16 v[0:3], v[170:173], v[230:233], v[0:3]
	s_setprio 0
	s_barrier
	v_or_b32_e32 v142, 0x18000, v141
	v_add_u32_e32 v146, 0x18400, v141
	v_add_u32_e32 v150, 0x18800, v141
	v_add_u32_e32 v154, 0x18c00, v141
	v_or_b32_e32 v158, 0x1c000, v141
	v_add_u32_e32 v162, 0x1c400, v141
	v_add_u32_e32 v166, 0x1c800, v141
	v_add_u32_e32 v170, 0x1cc00, v141
	ds_read_b128 v[142:145], v142
	ds_read_b128 v[146:149], v146
	ds_read_b128 v[150:153], v150
	ds_read_b128 v[154:157], v154
	ds_read_b128 v[158:161], v158
	ds_read_b128 v[162:165], v162
	ds_read_b128 v[166:169], v166
	ds_read_b128 v[170:173], v170
	s_add_u32 s62, s62, s42
	s_addc_u32 s63, s63, s43
	s_mov_b32 m0, s22
	v_lshl_add_u64 v[244:245], s[62:63], 0, v[134:135]
	ds_read_b128 v[174:177], v140 offset:32768
	ds_read_b128 v[178:181], v140 offset:33792
	ds_read_b128 v[182:185], v140 offset:34816
	ds_read_b128 v[186:189], v140 offset:35840
	ds_read_b128 v[190:193], v140 offset:36864
	ds_read_b128 v[202:205], v140 offset:37888
	ds_read_b128 v[206:209], v140 offset:38912
	ds_read_b128 v[230:233], v140 offset:39936
	global_load_lds_dwordx4 v[244:245], off
	v_lshl_add_u64 v[244:245], s[62:63], 0, v[132:133]
	s_mov_b32 m0, s23
	s_nop 0
	global_load_lds_dwordx4 v[244:245], off
	s_waitcnt vmcnt(8)
	s_waitcnt lgkmcnt(0)
	s_barrier
; #define PG8_STAGE(bufoff, gbase, voff) do { _Pragma("unroll") for (int _i = 0; _i < 2; ++_i) \
;         __builtin_amdgcn_global_load_lds((const unsigned*)((const char*)(gbase) + (voff)[_i]), (PG8_LAS unsigned*)(lds + (bufoff) + ldsw + _i * 8192), 16, 0, 0); } while (0)
; #define PG8_LDA(dst, b, h) do { _Pragma("unroll") for (int m = 0; m < 4; ++m) _Pragma("unroll") for (int k = 0; k < 2; ++k) dst[m][k] = *(const PG8_LAS bf16x8*)(lds + PG8_SA(b, h) + aoff + m * 2048 + k * 1024); } while (0)
; #define PG8_MMA(ai, bj, At, Bt) do { __builtin_amdgcn_s_setprio(1); _Pragma("unroll") for (int m = 0; m < 4; ++m) _Pragma("unroll") for (int n = 0; n < 2; ++n) _Pragma("unroll") for (int k = 0; k < 2; ++k) \
;         acc[ai][bj][m][n] = __builtin_amdgcn_mfma_f32_16x16x32_bf16(Bt[n][k], At[m][k], acc[ai][bj][m][n], 0, 0, 0); __builtin_amdgcn_s_setprio(0); } while (0)
; #define PG8_WAIT_V(n) asm volatile("s_waitcnt vmcnt(" #n ")" ::: "memory")
; #define PG8_WAIT_L(n) asm volatile("s_waitcnt lgkmcnt(" #n ")" ::: "memory")
; #define PG8_BAR __builtin_amdgcn_s_barrier()
; #define PG8_SCHED __builtin_amdgcn_sched_barrier(0)
; template <class Epi, class Sched, bool ALIGN_EPI = false, bool SP2 = false>
; __device__ __forceinline__ void gemm_phase(PG8_LAS unsigned char* lds, const Gemm g, const Sched& S, const Epi& E) {
;     ...
;             PG8_WAIT_V(8); PG8_WAIT_L(0); PG8_BAR; PG8_MMA(0, 0, At, B0); PG8_MMA(0, 1, At, B1); PG8_BAR; PG8_SCHED;
;             PG8_LDA(At, 1, 1); PG8_STAGE(PG8_SB(1, 0), b3, voffB); PG8_STAGE(PG8_SB(1, 1), b3 + hstep, voffB); PG8_STAGE(PG8_SA(1, 0), a3, voffA);
;             PG8_WAIT_V(8); PG8_WAIT_L(0); PG8_BAR; PG8_MMA(1, 0, At, B0); PG8_MMA(1, 1, At, B1); PG8_BAR; PG8_SCHED;
;     ...
;         if constexpr (ALIGN_EPI) { if (wr == 0) PG8_BAR; }
;         if constexpr (!Epi::AFTER_DRAIN) { E(acc, cur, wr, wc, fr, fq); S.done(cur); }
;         if (!has_next) break;
;         if constexpr (Epi::ACC_INIT) E.acc_init(ini, nxt);
	s_setprio 1
	s_waitcnt lgkmcnt(0)
	v_mfma_f32_16x16x32_bf16 v[126:129], v[142:145], v[174:177], v[126:129]
	v_mfma_f32_16x16x32_bf16 v[122:125], v[150:153], v[174:177], v[122:125]
	v_mfma_f32_16x16x32_bf16 v[118:121], v[142:145], v[182:185], v[118:121]
	v_mfma_f32_16x16x32_bf16 v[114:117], v[150:153], v[182:185], v[114:117]
	v_mfma_f32_16x16x32_bf16 v[110:113], v[142:145], v[190:193], v[110:113]
	v_mfma_f32_16x16x32_bf16 v[106:109], v[150:153], v[190:193], v[106:109]
	v_mfma_f32_16x16x32_bf16 v[102:105], v[142:145], v[206:209], v[102:105]
	v_mfma_f32_16x16x32_bf16 v[98:101], v[150:153], v[206:209], v[98:101]
	v_mfma_f32_16x16x32_bf16 v[126:129], v[146:149], v[178:181], v[126:129]
	v_mfma_f32_16x16x32_bf16 v[122:125], v[154:157], v[178:181], v[122:125]
	v_mfma_f32_16x16x32_bf16 v[118:121], v[146:149], v[186:189], v[118:121]
	v_mfma_f32_16x16x32_bf16 v[114:117], v[154:157], v[186:189], v[114:117]
	v_mfma_f32_16x16x32_bf16 v[110:113], v[146:149], v[202:205], v[110:113]
	v_mfma_f32_16x16x32_bf16 v[106:109], v[154:157], v[202:205], v[106:109]
	v_mfma_f32_16x16x32_bf16 v[102:105], v[146:149], v[230:233], v[102:105]
	v_mfma_f32_16x16x32_bf16 v[98:101], v[154:157], v[230:233], v[98:101]
	s_setprio 0
	s_setprio 1
	v_mfma_f32_16x16x32_bf16 v[68:71], v[158:161], v[174:177], v[68:71]
	v_mfma_f32_16x16x32_bf16 v[64:67], v[166:169], v[174:177], v[64:67]
	v_mfma_f32_16x16x32_bf16 v[60:63], v[158:161], v[182:185], v[60:63]
	v_mfma_f32_16x16x32_bf16 v[56:59], v[166:169], v[182:185], v[56:59]
	v_mfma_f32_16x16x32_bf16 v[52:55], v[158:161], v[190:193], v[52:55]
	v_mfma_f32_16x16x32_bf16 v[48:51], v[166:169], v[190:193], v[48:51]
	v_mfma_f32_16x16x32_bf16 v[44:47], v[158:161], v[206:209], v[44:47]
	v_mfma_f32_16x16x32_bf16 v[40:43], v[166:169], v[206:209], v[40:43]
	v_mfma_f32_16x16x32_bf16 v[68:71], v[162:165], v[178:181], v[68:71]
	v_mfma_f32_16x16x32_bf16 v[64:67], v[170:173], v[178:181], v[64:67]
	v_mfma_f32_16x16x32_bf16 v[60:63], v[162:165], v[186:189], v[60:63]
	v_mfma_f32_16x16x32_bf16 v[56:59], v[170:173], v[186:189], v[56:59]
	v_mfma_f32_16x16x32_bf16 v[52:55], v[162:165], v[202:205], v[52:55]
	v_mfma_f32_16x16x32_bf16 v[48:51], v[170:173], v[202:205], v[48:51]
	v_mfma_f32_16x16x32_bf16 v[44:47], v[162:165], v[230:233], v[44:47]
	v_mfma_f32_16x16x32_bf16 v[40:43], v[170:173], v[230:233], v[40:43]
	s_setprio 0
	s_barrier
	s_mov_b32 m0, s31
	v_lshl_add_u64 v[210:211], v[210:211], 0, s[8:9]
	ds_read_b128 v[174:177], v140 offset:49152
	ds_read_b128 v[178:181], v140 offset:50176
	ds_read_b128 v[182:185], v140 offset:51200
	ds_read_b128 v[186:189], v140 offset:52224
	ds_read_b128 v[190:193], v140 offset:53248
	ds_read_b128 v[202:205], v140 offset:54272
	ds_read_b128 v[206:209], v140 offset:55296
	ds_read_b128 v[230:233], v140 offset:56320
	global_load_lds_dwordx4 v[210:211], off
	v_lshl_add_u64 v[210:211], v[234:235], 0, s[8:9]
	s_mov_b32 m0, s34
	s_nop 0
	global_load_lds_dwordx4 v[210:211], off
	v_lshl_add_u64 v[210:211], v[236:237], 0, s[8:9]
	s_mov_b32 m0, s65
	s_nop 0
	global_load_lds_dwordx4 v[210:211], off
	v_lshl_add_u64 v[210:211], v[238:239], 0, s[8:9]
	s_mov_b32 m0, s66
	s_nop 0
	global_load_lds_dwordx4 v[210:211], off
	v_lshl_add_u64 v[210:211], v[240:241], 0, s[8:9]
	s_mov_b32 m0, s36
	s_nop 0
	global_load_lds_dwordx4 v[210:211], off
	v_lshl_add_u64 v[210:211], v[242:243], 0, s[8:9]
	s_mov_b32 m0, s64
	s_nop 0
	global_load_lds_dwordx4 v[210:211], off
	s_waitcnt vmcnt(8)
	s_waitcnt lgkmcnt(0)
	s_barrier
	s_setprio 1
	s_waitcnt lgkmcnt(0)
	v_mfma_f32_16x16x32_bf16 v[92:95], v[142:145], v[174:177], v[92:95]
	v_mfma_f32_16x16x32_bf16 v[88:91], v[150:153], v[174:177], v[88:91]
	v_mfma_f32_16x16x32_bf16 v[84:87], v[142:145], v[182:185], v[84:87]
	v_mfma_f32_16x16x32_bf16 v[80:83], v[150:153], v[182:185], v[80:83]
	v_mfma_f32_16x16x32_bf16 v[76:79], v[142:145], v[190:193], v[76:79]
	v_mfma_f32_16x16x32_bf16 v[72:75], v[150:153], v[190:193], v[72:75]
	v_mfma_f32_16x16x32_bf16 v[12:15], v[142:145], v[206:209], v[12:15]
	v_mfma_f32_16x16x32_bf16 v[8:11], v[150:153], v[206:209], v[8:11]
	v_mfma_f32_16x16x32_bf16 v[92:95], v[146:149], v[178:181], v[92:95]
	v_mfma_f32_16x16x32_bf16 v[88:91], v[154:157], v[178:181], v[88:91]
	v_mfma_f32_16x16x32_bf16 v[84:87], v[146:149], v[186:189], v[84:87]
	v_mfma_f32_16x16x32_bf16 v[80:83], v[154:157], v[186:189], v[80:83]
	v_mfma_f32_16x16x32_bf16 v[76:79], v[146:149], v[202:205], v[76:79]
	v_mfma_f32_16x16x32_bf16 v[72:75], v[154:157], v[202:205], v[72:75]
	v_mfma_f32_16x16x32_bf16 v[12:15], v[146:149], v[230:233], v[12:15]
	v_mfma_f32_16x16x32_bf16 v[8:11], v[154:157], v[230:233], v[8:11]
	s_setprio 0
	s_setprio 1
	v_mfma_f32_16x16x32_bf16 v[36:39], v[158:161], v[174:177], v[36:39]
	v_mfma_f32_16x16x32_bf16 v[32:35], v[166:169], v[174:177], v[32:35]
	v_mfma_f32_16x16x32_bf16 v[28:31], v[158:161], v[182:185], v[28:31]
	v_mfma_f32_16x16x32_bf16 v[24:27], v[166:169], v[182:185], v[24:27]
	v_mfma_f32_16x16x32_bf16 v[20:23], v[158:161], v[190:193], v[20:23]
	v_mfma_f32_16x16x32_bf16 v[16:19], v[166:169], v[190:193], v[16:19]
	v_mfma_f32_16x16x32_bf16 v[4:7], v[158:161], v[206:209], v[4:7]
	v_mfma_f32_16x16x32_bf16 v[0:3], v[166:169], v[206:209], v[0:3]
	v_mfma_f32_16x16x32_bf16 v[36:39], v[162:165], v[178:181], v[36:39]
	v_mfma_f32_16x16x32_bf16 v[32:35], v[170:173], v[178:181], v[32:35]
	v_mfma_f32_16x16x32_bf16 v[28:31], v[162:165], v[186:189], v[28:31]
	v_mfma_f32_16x16x32_bf16 v[24:27], v[170:173], v[186:189], v[24:27]
	v_mfma_f32_16x16x32_bf16 v[20:23], v[162:165], v[202:205], v[20:23]
	v_mfma_f32_16x16x32_bf16 v[16:19], v[170:173], v[202:205], v[16:19]
	v_mfma_f32_16x16x32_bf16 v[4:7], v[162:165], v[230:233], v[4:7]
	v_mfma_f32_16x16x32_bf16 v[0:3], v[170:173], v[230:233], v[0:3]
	s_setprio 0
	s_barrier
	s_add_u32 s60, s60, 0x100
	s_addc_u32 s61, s61, 0
	s_add_u32 s55, s55, 0x100
	s_addc_u32 s73, s73, 0
	s_cmp_ge_i32 s74, s67
	s_mov_b32 s62, s74
	s_cbranch_scc0 .LBB0_399
	s_and_b64 vcc, exec, s[50:51]
	s_cbranch_vccz .LBB0_410
.LBB0_401:
	s_barrier
	s_cmp_lg_u64 s[38:39], 0
	s_cbranch_scc1 .Lnb_a
	s_lshl_b32 s100, s70, 8
	s_ashr_i32 s101, s100, 31
	s_lshl_b64 s[100:101], s[100:101], 2
	s_add_u32 s100, s0, s100
	s_addc_u32 s101, s6, s101
	s_cmp_lt_i32 s70, 8
	s_cselect_b32 s98, 0, 32
	s_add_u32 s100, s100, s98
	s_addc_u32 s101, s101, 0
	v_readfirstlane_b32 s98, v212
	s_nop 0
	s_lshl_b32 s98, s98, 1
	s_and_b32 s98, s98, 0x180
	s_add_u32 s100, s100, s98
	s_addc_u32 s101, s101, 0
	v_lshlrev_b32_e32 v190, 1, v212
	v_and_b32_e32 v190, 0x60, v190
	global_load_dwordx4 v[182:185], v190, s[100:101] offset:16
	global_load_dwordx4 v[186:189], v190, s[100:101]
	global_load_dwordx4 v[174:177], v190, s[100:101] offset:528
	global_load_dwordx4 v[178:181], v190, s[100:101] offset:512
.Lnb_a:
	s_cmp_lt_i32 s72, 12
	s_mov_b64 s[60:61], -1
	s_cbranch_scc1 .LBB0_411

; template <class Epi, class Sched, bool ALIGN_EPI = false, bool SP2 = false>
; __device__ __forceinline__ void gemm_phase(PG8_LAS unsigned char* lds, const Gemm g, const Sched& S, const Epi& E) {
;     ...
;         if (!has_next) break;
;         if constexpr (Epi::ACC_INIT) E.acc_init(ini, nxt);
.LBB0_404:
	s_and_b64 vcc, exec, s[38:39]
	s_mov_b64 s[38:39], -1
	s_cbranch_vccnz .LBB0_392
	s_andn2_b64 vcc, exec, s[46:47]
	s_cbranch_vccnz .LBB0_391
	s_barrier
	s_branch .LBB0_391

;     __device__ __forceinline__ void acc_init(f32x4 (&ini)[2][2], const Unit& u) const {
;         int t__ = threadIdx.x; asm volatile("" : "+v"(t__)); const int wid__ = __builtin_amdgcn_readfirstlane(t__ >> 6), wc = wid__ & 3, fq = (t__ & 63) >> 4;
;         const int pn = u.pn; const float* bp = bias + pn * BM + (pn >= 8 ? 8 : 0) + wc * 32 + 8 * fq;
; #pragma unroll
;         for (int bj = 0; bj < 2; ++bj)
; #pragma unroll
;             for (int n = 0; n < 2; ++n) ini[bj][n] = *(const f32x4*)(bp + bj * HALF + 4 * n);
.LBB0_410:
	s_cmp_lg_u64 s[38:39], 0
	s_cbranch_scc1 .Lnb_b
	s_lshl_b32 s100, s70, 8
	s_ashr_i32 s101, s100, 31
	s_lshl_b64 s[100:101], s[100:101], 2
	s_add_u32 s100, s0, s100
	s_addc_u32 s101, s6, s101
	s_cmp_lt_i32 s70, 8
	s_cselect_b32 s98, 0, 32
	s_add_u32 s100, s100, s98
	s_addc_u32 s101, s101, 0
	v_readfirstlane_b32 s98, v212
	s_nop 0
	s_lshl_b32 s98, s98, 1
	s_and_b32 s98, s98, 0x180
	s_add_u32 s100, s100, s98
	s_addc_u32 s101, s101, 0
	v_lshlrev_b32_e32 v190, 1, v212
	v_and_b32_e32 v190, 0x60, v190
	global_load_dwordx4 v[182:185], v190, s[100:101] offset:16
	global_load_dwordx4 v[186:189], v190, s[100:101]
	global_load_dwordx4 v[174:177], v190, s[100:101] offset:528
	global_load_dwordx4 v[178:181], v190, s[100:101] offset:512
